# strategy 9: first K-loop iteration peeled, first MFMA of every accumulator takes C=0, the 128 accumulator-zeroing moves per GEMM unit deleted
# speedup vs baseline: 1.0014x; 1.0014x over previous
; #define PG8_STAGE(bufoff, gbase, voff) do { _Pragma("unroll") for (int _i = 0; _i < 2; ++_i) \
;         __builtin_amdgcn_global_load_lds((const unsigned*)((const char*)(gbase) + (voff)[_i]), (LAS unsigned*)(lds + (bufoff) + ldsw + _i * 8192), 16, 0, 0); } while (0)
; #define PG8_LDA(dst, b, h) do { _Pragma("unroll") for (int m = 0; m < 4; ++m) _Pragma("unroll") for (int k = 0; k < 2; ++k) dst[m][k] = *(const LAS bf16x8*)(lds + PG8_SA(b, h) + aoff + m * 2048 + k * 1024); } while (0)
; #define PG8_LDB(dst, b, h) do { _Pragma("unroll") for (int n = 0; n < 2; ++n) _Pragma("unroll") for (int k = 0; k < 2; ++k) dst[n][k] = *(const LAS bf16x8*)(lds + PG8_SB(b, h) + boff + n * 2048 + k * 1024); } while (0)
; #define PG8_MMA(ai, bj, At, Bt) do { __builtin_amdgcn_s_setprio(1); _Pragma("unroll") for (int m = 0; m < 4; ++m) _Pragma("unroll") for (int n = 0; n < 2; ++n) _Pragma("unroll") for (int k = 0; k < 2; ++k) \
;         acc[ai][bj][m][n] = __builtin_amdgcn_mfma_f32_16x16x32_bf16(Bt[n][k], At[m][k], acc[ai][bj][m][n], 0, 0, 0); __builtin_amdgcn_s_setprio(0); } while (0)
; template <class Epi>
; __device__ __forceinline__ void gemm_phase(LAS unsigned char* lds, const Gemm g, const StaticOrder& S, const Epi& E) {
;     ...
;         for (int t = 0; t < nt; t += 2) {
;             const bool last = (t == nt - 2);
;             const char* a1 = cA + (size_t)(t + 1) * kstep;
;             const char* a2 = last ? nA : cA + (size_t)(t + 2) * kstep; const char* b2 = last ? nB : cB + (size_t)(t + 2) * kstep;
;             const char* a3 = a2 + kstep; const char* b3 = b2 + kstep;
;             PG8_LDB(B0, 0, 0); PG8_LDB(B1, 0, 1); PG8_SCHED; PG8_LDA(At, 0, 0); PG8_STAGE(PG8_SA(1, 1), a1 + hA, voffA);
;             PG8_WAIT_V(8); PG8_WAIT_L(0); PG8_BAR; PG8_MMA(0, 0, At, B0); PG8_MMA(0, 1, At, B1); PG8_BAR; PG8_SCHED;
;             PG8_LDA(At, 0, 1); PG8_STAGE(PG8_SB(0, 0), b2, voffB); PG8_STAGE(PG8_SB(0, 1), b2 + hB, voffB); PG8_STAGE(PG8_SA(0, 0), a2, voffA);
;             PG8_WAIT_V(8); PG8_WAIT_L(0); PG8_BAR; PG8_MMA(1, 0, At, B0); PG8_MMA(1, 1, At, B1); PG8_BAR; PG8_SCHED;
;     ...
; #pragma unroll
;         for (int a = 0; a < 2; ++a)
; #pragma unroll
;             for (int b = 0; b < 2; ++b)
; #pragma unroll
;                 for (int m = 0; m < 4; ++m)
; #pragma unroll
;                     for (int n = 0; n < 2; ++n) acc[a][b][m][n] = (f32x4){0.f, 0.f, 0.f, 0.f};
.LBB0_341:
	s_add_u32 s4, s36, 0x80
	s_addc_u32 s5, s37, 0
	s_add_u32 s36, s34, 0x100
	s_addc_u32 s37, s35, 0
	s_mov_b32 s34, 0
	s_waitcnt lgkmcnt(0)
	s_nop 0
.Lpeel_342:
	s_add_i32 m0, s42, 0xc000
	ds_read_b128 v[128:131], v240
	ds_read_b128 v[132:135], v240 offset:1024
	ds_read_b128 v[136:139], v240 offset:2048
	ds_read_b128 v[140:143], v240 offset:3072
	ds_read_b128 v[144:147], v240 offset:16384
	ds_read_b128 v[148:151], v240 offset:17408
	ds_read_b128 v[152:155], v240 offset:18432
	ds_read_b128 v[156:159], v240 offset:19456
	ds_read_b128 v[160:163], v191
	ds_read_b128 v[180:183], v191 offset:1024
	ds_read_b128 v[184:187], v191 offset:2048
	ds_read_b128 v[192:195], v191 offset:3072
	ds_read_b128 v[206:209], v191 offset:4096
	ds_read_b128 v[210:213], v191 offset:5120
	ds_read_b128 v[214:217], v191 offset:6144
	ds_read_b128 v[218:221], v191 offset:7168
	global_load_lds_dwordx4 v176, s[4:5]
	s_add_i32 m0, s42, 0xe000
	s_nop 0
	global_load_lds_dwordx4 v178, s[4:5]
	s_add_i32 s56, s34, 2
	s_add_u32 s57, s4, 0x80
	s_addc_u32 s35, s5, 0
	s_add_i32 s60, 0, 0x10000
	s_cmp_eq_u32 s50, s34
	s_cselect_b32 s35, s29, s35
	s_cselect_b32 s34, s28, s57
	s_cselect_b32 s59, s31, s37
	s_cselect_b32 s58, s30, s36
	s_add_i32 s57, 0, 0x14000
	s_waitcnt vmcnt(8)
	s_waitcnt lgkmcnt(0)
	s_barrier
	s_setprio 1
	s_waitcnt lgkmcnt(0)
	v_mfma_f32_16x16x32_bf16 v[124:127], v[128:131], v[160:163], 0
	v_mfma_f32_16x16x32_bf16 v[120:123], v[136:139], v[160:163], 0
	v_mfma_f32_16x16x32_bf16 v[112:115], v[128:131], v[184:187], 0
	v_mfma_f32_16x16x32_bf16 v[104:107], v[136:139], v[184:187], 0
	v_mfma_f32_16x16x32_bf16 v[96:99], v[128:131], v[206:209], 0
	v_mfma_f32_16x16x32_bf16 v[88:91], v[136:139], v[206:209], 0
	v_mfma_f32_16x16x32_bf16 v[80:83], v[128:131], v[214:217], 0
	v_mfma_f32_16x16x32_bf16 v[72:75], v[136:139], v[214:217], 0
	v_mfma_f32_16x16x32_bf16 v[124:127], v[132:135], v[180:183], v[124:127]
	v_mfma_f32_16x16x32_bf16 v[120:123], v[140:143], v[180:183], v[120:123]
	v_mfma_f32_16x16x32_bf16 v[112:115], v[132:135], v[192:195], v[112:115]
	v_mfma_f32_16x16x32_bf16 v[104:107], v[140:143], v[192:195], v[104:107]
	v_mfma_f32_16x16x32_bf16 v[96:99], v[132:135], v[210:213], v[96:99]
	v_mfma_f32_16x16x32_bf16 v[88:91], v[140:143], v[210:213], v[88:91]
	v_mfma_f32_16x16x32_bf16 v[80:83], v[132:135], v[218:221], v[80:83]
	v_mfma_f32_16x16x32_bf16 v[72:75], v[140:143], v[218:221], v[72:75]
	s_setprio 0
	s_setprio 1
	v_mfma_f32_16x16x32_bf16 v[116:119], v[144:147], v[160:163], 0
	v_mfma_f32_16x16x32_bf16 v[108:111], v[152:155], v[160:163], 0
	v_mfma_f32_16x16x32_bf16 v[100:103], v[144:147], v[184:187], 0
	v_mfma_f32_16x16x32_bf16 v[92:95], v[152:155], v[184:187], 0
	v_mfma_f32_16x16x32_bf16 v[84:87], v[144:147], v[206:209], 0
	v_mfma_f32_16x16x32_bf16 v[76:79], v[152:155], v[206:209], 0
	v_mfma_f32_16x16x32_bf16 v[68:71], v[144:147], v[214:217], 0
	v_mfma_f32_16x16x32_bf16 v[64:67], v[152:155], v[214:217], 0
	v_mfma_f32_16x16x32_bf16 v[116:119], v[148:151], v[180:183], v[116:119]
	v_mfma_f32_16x16x32_bf16 v[108:111], v[156:159], v[180:183], v[108:111]
	v_mfma_f32_16x16x32_bf16 v[100:103], v[148:151], v[192:195], v[100:103]
	v_mfma_f32_16x16x32_bf16 v[92:95], v[156:159], v[192:195], v[92:95]
	v_mfma_f32_16x16x32_bf16 v[84:87], v[148:151], v[210:213], v[84:87]
	v_mfma_f32_16x16x32_bf16 v[76:79], v[156:159], v[210:213], v[76:79]
	v_mfma_f32_16x16x32_bf16 v[68:71], v[148:151], v[218:221], v[68:71]
	v_mfma_f32_16x16x32_bf16 v[64:67], v[156:159], v[218:221], v[64:67]
	s_setprio 0
	s_barrier
	ds_read_b128 v[160:163], v191 offset:16384
	ds_read_b128 v[180:183], v191 offset:17408
	ds_read_b128 v[184:187], v191 offset:18432
	ds_read_b128 v[192:195], v191 offset:19456
	ds_read_b128 v[206:209], v191 offset:20480
	ds_read_b128 v[210:213], v191 offset:21504
	ds_read_b128 v[214:217], v191 offset:22528
	ds_read_b128 v[218:221], v191 offset:23552
	s_add_i32 s60, s60, s41
	s_mov_b32 m0, s60
	s_add_i32 s57, s57, s41
	global_load_lds_dwordx4 v168, s[58:59]
	s_add_i32 m0, s60, 0x2000
	s_nop 0
	global_load_lds_dwordx4 v174, s[58:59]
	s_add_u32 s58, s58, s16
	s_addc_u32 s59, s59, 0
	s_mov_b32 m0, s57
	s_nop 0
	global_load_lds_dwordx4 v168, s[58:59]
	s_add_i32 m0, s57, 0x2000
	s_nop 0
	global_load_lds_dwordx4 v174, s[58:59]
	s_mov_b32 m0, s42
	s_nop 0
	global_load_lds_dwordx4 v168, s[34:35]
	s_mov_b32 m0, s43
	s_nop 0
	global_load_lds_dwordx4 v174, s[34:35]
	s_waitcnt vmcnt(8)
	s_waitcnt lgkmcnt(0)
	s_barrier
	s_setprio 1
	s_waitcnt lgkmcnt(0)
	v_mfma_f32_16x16x32_bf16 v[60:63], v[128:131], v[160:163], 0
	v_mfma_f32_16x16x32_bf16 v[56:59], v[136:139], v[160:163], 0
	v_mfma_f32_16x16x32_bf16 v[48:51], v[128:131], v[184:187], 0
	v_mfma_f32_16x16x32_bf16 v[40:43], v[136:139], v[184:187], 0
	v_mfma_f32_16x16x32_bf16 v[32:35], v[128:131], v[206:209], 0
	v_mfma_f32_16x16x32_bf16 v[24:27], v[136:139], v[206:209], 0
	v_mfma_f32_16x16x32_bf16 v[16:19], v[128:131], v[214:217], 0
	v_mfma_f32_16x16x32_bf16 v[8:11], v[136:139], v[214:217], 0
	v_mfma_f32_16x16x32_bf16 v[60:63], v[132:135], v[180:183], v[60:63]
	v_mfma_f32_16x16x32_bf16 v[56:59], v[140:143], v[180:183], v[56:59]
	v_mfma_f32_16x16x32_bf16 v[48:51], v[132:135], v[192:195], v[48:51]
	v_mfma_f32_16x16x32_bf16 v[40:43], v[140:143], v[192:195], v[40:43]
	v_mfma_f32_16x16x32_bf16 v[32:35], v[132:135], v[210:213], v[32:35]
	v_mfma_f32_16x16x32_bf16 v[24:27], v[140:143], v[210:213], v[24:27]
	v_mfma_f32_16x16x32_bf16 v[16:19], v[132:135], v[218:221], v[16:19]
	v_mfma_f32_16x16x32_bf16 v[8:11], v[140:143], v[218:221], v[8:11]
	s_setprio 0
	s_setprio 1
	v_mfma_f32_16x16x32_bf16 v[52:55], v[144:147], v[160:163], 0
	v_mfma_f32_16x16x32_bf16 v[44:47], v[152:155], v[160:163], 0
	v_mfma_f32_16x16x32_bf16 v[36:39], v[144:147], v[184:187], 0
	v_mfma_f32_16x16x32_bf16 v[28:31], v[152:155], v[184:187], 0
	v_mfma_f32_16x16x32_bf16 v[20:23], v[144:147], v[206:209], 0
	v_mfma_f32_16x16x32_bf16 v[12:15], v[152:155], v[206:209], 0
	v_mfma_f32_16x16x32_bf16 v[4:7], v[144:147], v[214:217], 0
	v_mfma_f32_16x16x32_bf16 v[0:3], v[152:155], v[214:217], 0
	v_mfma_f32_16x16x32_bf16 v[52:55], v[148:151], v[180:183], v[52:55]
	v_mfma_f32_16x16x32_bf16 v[44:47], v[156:159], v[180:183], v[44:47]
	v_mfma_f32_16x16x32_bf16 v[36:39], v[148:151], v[192:195], v[36:39]
	v_mfma_f32_16x16x32_bf16 v[28:31], v[156:159], v[192:195], v[28:31]
	v_mfma_f32_16x16x32_bf16 v[20:23], v[148:151], v[210:213], v[20:23]
	v_mfma_f32_16x16x32_bf16 v[12:15], v[156:159], v[210:213], v[12:15]
	v_mfma_f32_16x16x32_bf16 v[4:7], v[148:151], v[218:221], v[4:7]
	v_mfma_f32_16x16x32_bf16 v[0:3], v[156:159], v[218:221], v[0:3]
	s_setprio 0
	s_barrier
; #define PG8_STAGE(bufoff, gbase, voff) do { _Pragma("unroll") for (int _i = 0; _i < 2; ++_i) \
;         __builtin_amdgcn_global_load_lds((const unsigned*)((const char*)(gbase) + (voff)[_i]), (LAS unsigned*)(lds + (bufoff) + ldsw + _i * 8192), 16, 0, 0); } while (0)
; #define PG8_LDA(dst, b, h) do { _Pragma("unroll") for (int m = 0; m < 4; ++m) _Pragma("unroll") for (int k = 0; k < 2; ++k) dst[m][k] = *(const LAS bf16x8*)(lds + PG8_SA(b, h) + aoff + m * 2048 + k * 1024); } while (0)
; #define PG8_LDB(dst, b, h) do { _Pragma("unroll") for (int n = 0; n < 2; ++n) _Pragma("unroll") for (int k = 0; k < 2; ++k) dst[n][k] = *(const LAS bf16x8*)(lds + PG8_SB(b, h) + boff + n * 2048 + k * 1024); } while (0)
; #define PG8_MMA(ai, bj, At, Bt) do { __builtin_amdgcn_s_setprio(1); _Pragma("unroll") for (int m = 0; m < 4; ++m) _Pragma("unroll") for (int n = 0; n < 2; ++n) _Pragma("unroll") for (int k = 0; k < 2; ++k) \
;         acc[ai][bj][m][n] = __builtin_amdgcn_mfma_f32_16x16x32_bf16(Bt[n][k], At[m][k], acc[ai][bj][m][n], 0, 0, 0); __builtin_amdgcn_s_setprio(0); } while (0)
; #define PG8_WAIT_V(n) asm volatile("s_waitcnt vmcnt(" #n ")" ::: "memory")
; #define PG8_WAIT_L(n) asm volatile("s_waitcnt lgkmcnt(" #n ")" ::: "memory")
; #define PG8_BAR __builtin_amdgcn_s_barrier()
; #define PG8_SCHED __builtin_amdgcn_sched_barrier(0)
; template <class Epi>
; __device__ __forceinline__ void gemm_phase(LAS unsigned char* lds, const Gemm g, const StaticOrder& S, const Epi& E) {
;     ...
;             PG8_LDB(B0, 1, 0); PG8_LDB(B1, 1, 1); PG8_SCHED; PG8_LDA(At, 1, 0); PG8_STAGE(PG8_SA(0, 1), a2 + hA, voffA);
;             PG8_WAIT_V(8); PG8_WAIT_L(0); PG8_BAR; PG8_MMA(0, 0, At, B0); PG8_MMA(0, 1, At, B1); PG8_BAR; PG8_SCHED;
;             PG8_LDA(At, 1, 1); PG8_STAGE(PG8_SB(1, 0), b3, voffB); PG8_STAGE(PG8_SB(1, 1), b3 + hB, voffB); PG8_STAGE(PG8_SA(1, 0), a3, voffA);
;             PG8_WAIT_V(8); PG8_WAIT_L(0); PG8_BAR; PG8_MMA(1, 0, At, B0); PG8_MMA(1, 1, At, B1); PG8_BAR; PG8_SCHED;
;         }
	ds_read_b128 v[128:131], v240 offset:32768
	ds_read_b128 v[132:135], v240 offset:33792
	ds_read_b128 v[136:139], v240 offset:34816
	ds_read_b128 v[140:143], v240 offset:35840
	ds_read_b128 v[144:147], v240 offset:49152
	ds_read_b128 v[148:151], v240 offset:50176
	ds_read_b128 v[152:155], v240 offset:51200
	ds_read_b128 v[156:159], v240 offset:52224
	ds_read_b128 v[160:163], v191 offset:32768
	ds_read_b128 v[180:183], v191 offset:33792
	ds_read_b128 v[184:187], v191 offset:34816
	ds_read_b128 v[192:195], v191 offset:35840
	ds_read_b128 v[206:209], v191 offset:36864
	ds_read_b128 v[210:213], v191 offset:37888
	ds_read_b128 v[214:217], v191 offset:38912
	ds_read_b128 v[218:221], v191 offset:39936
	s_add_u32 s34, s34, s16
	s_addc_u32 s35, s35, 0
	s_mov_b32 m0, s44
	s_add_i32 s60, 0, 0x18000
	global_load_lds_dwordx4 v168, s[34:35]
	s_mov_b32 m0, s45
	s_nop 0
	global_load_lds_dwordx4 v174, s[34:35]
	s_waitcnt vmcnt(8)
	s_waitcnt lgkmcnt(0)
	s_barrier
	s_setprio 1
	s_waitcnt lgkmcnt(0)
	v_mfma_f32_16x16x32_bf16 v[124:127], v[128:131], v[160:163], v[124:127]
	v_mfma_f32_16x16x32_bf16 v[120:123], v[136:139], v[160:163], v[120:123]
	v_mfma_f32_16x16x32_bf16 v[112:115], v[128:131], v[184:187], v[112:115]
	v_mfma_f32_16x16x32_bf16 v[104:107], v[136:139], v[184:187], v[104:107]
	v_mfma_f32_16x16x32_bf16 v[96:99], v[128:131], v[206:209], v[96:99]
	v_mfma_f32_16x16x32_bf16 v[88:91], v[136:139], v[206:209], v[88:91]
	v_mfma_f32_16x16x32_bf16 v[80:83], v[128:131], v[214:217], v[80:83]
	v_mfma_f32_16x16x32_bf16 v[72:75], v[136:139], v[214:217], v[72:75]
	v_mfma_f32_16x16x32_bf16 v[124:127], v[132:135], v[180:183], v[124:127]
	v_mfma_f32_16x16x32_bf16 v[120:123], v[140:143], v[180:183], v[120:123]
	v_mfma_f32_16x16x32_bf16 v[112:115], v[132:135], v[192:195], v[112:115]
	v_mfma_f32_16x16x32_bf16 v[104:107], v[140:143], v[192:195], v[104:107]
	v_mfma_f32_16x16x32_bf16 v[96:99], v[132:135], v[210:213], v[96:99]
	v_mfma_f32_16x16x32_bf16 v[88:91], v[140:143], v[210:213], v[88:91]
	v_mfma_f32_16x16x32_bf16 v[80:83], v[132:135], v[218:221], v[80:83]
	v_mfma_f32_16x16x32_bf16 v[72:75], v[140:143], v[218:221], v[72:75]
	s_setprio 0
	s_setprio 1
	v_mfma_f32_16x16x32_bf16 v[116:119], v[144:147], v[160:163], v[116:119]
	v_mfma_f32_16x16x32_bf16 v[108:111], v[152:155], v[160:163], v[108:111]
	v_mfma_f32_16x16x32_bf16 v[100:103], v[144:147], v[184:187], v[100:103]
	v_mfma_f32_16x16x32_bf16 v[92:95], v[152:155], v[184:187], v[92:95]
	v_mfma_f32_16x16x32_bf16 v[84:87], v[144:147], v[206:209], v[84:87]
	v_mfma_f32_16x16x32_bf16 v[76:79], v[152:155], v[206:209], v[76:79]
	v_mfma_f32_16x16x32_bf16 v[68:71], v[144:147], v[214:217], v[68:71]
	v_mfma_f32_16x16x32_bf16 v[64:67], v[152:155], v[214:217], v[64:67]
	v_mfma_f32_16x16x32_bf16 v[116:119], v[148:151], v[180:183], v[116:119]
	v_mfma_f32_16x16x32_bf16 v[108:111], v[156:159], v[180:183], v[108:111]
	v_mfma_f32_16x16x32_bf16 v[100:103], v[148:151], v[192:195], v[100:103]
	v_mfma_f32_16x16x32_bf16 v[92:95], v[156:159], v[192:195], v[92:95]
	v_mfma_f32_16x16x32_bf16 v[84:87], v[148:151], v[210:213], v[84:87]
	v_mfma_f32_16x16x32_bf16 v[76:79], v[156:159], v[210:213], v[76:79]
	v_mfma_f32_16x16x32_bf16 v[68:71], v[148:151], v[218:221], v[68:71]
	v_mfma_f32_16x16x32_bf16 v[64:67], v[156:159], v[218:221], v[64:67]
	s_setprio 0
	s_barrier
	ds_read_b128 v[160:163], v191 offset:49152
	ds_read_b128 v[180:183], v191 offset:50176
	ds_read_b128 v[184:187], v191 offset:51200
	ds_read_b128 v[192:195], v191 offset:52224
	ds_read_b128 v[206:209], v191 offset:53248
	ds_read_b128 v[210:213], v191 offset:54272
	ds_read_b128 v[214:217], v191 offset:55296
	ds_read_b128 v[218:221], v191 offset:56320
	s_add_i32 s60, s60, s41
	s_add_i32 m0, s60, 0x4000
	s_nop 0
	global_load_lds_dwordx4 v241, s[58:59]
	s_add_i32 m0, s60, 0x6000
	s_nop 0
	global_load_lds_dwordx4 v242, s[58:59]
	s_sub_u32 s58, s58, s16
	s_subb_u32 s59, s59, 0
	s_mov_b32 m0, s60
	s_nop 0
	global_load_lds_dwordx4 v241, s[58:59]
	s_add_i32 m0, s60, 0x2000
	s_nop 0
	global_load_lds_dwordx4 v242, s[58:59]
	s_sub_u32 s34, s34, s16
	s_subb_u32 s35, s35, 0
	s_mov_b32 m0, s48
	s_nop 0
	global_load_lds_dwordx4 v241, s[34:35]
	s_mov_b32 m0, s49
	s_nop 0
	global_load_lds_dwordx4 v242, s[34:35]
	s_waitcnt vmcnt(8)
	s_waitcnt lgkmcnt(0)
	s_barrier
	s_setprio 1
	s_waitcnt lgkmcnt(0)
	v_mfma_f32_16x16x32_bf16 v[60:63], v[128:131], v[160:163], v[60:63]
	v_mfma_f32_16x16x32_bf16 v[56:59], v[136:139], v[160:163], v[56:59]
	v_mfma_f32_16x16x32_bf16 v[48:51], v[128:131], v[184:187], v[48:51]
	v_mfma_f32_16x16x32_bf16 v[40:43], v[136:139], v[184:187], v[40:43]
	v_mfma_f32_16x16x32_bf16 v[32:35], v[128:131], v[206:209], v[32:35]
	v_mfma_f32_16x16x32_bf16 v[24:27], v[136:139], v[206:209], v[24:27]
	v_mfma_f32_16x16x32_bf16 v[16:19], v[128:131], v[214:217], v[16:19]
	v_mfma_f32_16x16x32_bf16 v[8:11], v[136:139], v[214:217], v[8:11]
	v_mfma_f32_16x16x32_bf16 v[60:63], v[132:135], v[180:183], v[60:63]
	v_mfma_f32_16x16x32_bf16 v[56:59], v[140:143], v[180:183], v[56:59]
	v_mfma_f32_16x16x32_bf16 v[48:51], v[132:135], v[192:195], v[48:51]
	v_mfma_f32_16x16x32_bf16 v[40:43], v[140:143], v[192:195], v[40:43]
	v_mfma_f32_16x16x32_bf16 v[32:35], v[132:135], v[210:213], v[32:35]
	v_mfma_f32_16x16x32_bf16 v[24:27], v[140:143], v[210:213], v[24:27]
	v_mfma_f32_16x16x32_bf16 v[16:19], v[132:135], v[218:221], v[16:19]
	v_mfma_f32_16x16x32_bf16 v[8:11], v[140:143], v[218:221], v[8:11]
	s_setprio 0
	s_setprio 1
	v_mfma_f32_16x16x32_bf16 v[52:55], v[144:147], v[160:163], v[52:55]
	v_mfma_f32_16x16x32_bf16 v[44:47], v[152:155], v[160:163], v[44:47]
	v_mfma_f32_16x16x32_bf16 v[36:39], v[144:147], v[184:187], v[36:39]
	v_mfma_f32_16x16x32_bf16 v[28:31], v[152:155], v[184:187], v[28:31]
	v_mfma_f32_16x16x32_bf16 v[20:23], v[144:147], v[206:209], v[20:23]
	v_mfma_f32_16x16x32_bf16 v[12:15], v[152:155], v[206:209], v[12:15]
	v_mfma_f32_16x16x32_bf16 v[4:7], v[144:147], v[214:217], v[4:7]
	v_mfma_f32_16x16x32_bf16 v[0:3], v[152:155], v[214:217], v[0:3]
	v_mfma_f32_16x16x32_bf16 v[52:55], v[148:151], v[180:183], v[52:55]
	v_mfma_f32_16x16x32_bf16 v[44:47], v[156:159], v[180:183], v[44:47]
	v_mfma_f32_16x16x32_bf16 v[36:39], v[148:151], v[192:195], v[36:39]
	v_mfma_f32_16x16x32_bf16 v[28:31], v[156:159], v[192:195], v[28:31]
	v_mfma_f32_16x16x32_bf16 v[20:23], v[148:151], v[210:213], v[20:23]
	v_mfma_f32_16x16x32_bf16 v[12:15], v[156:159], v[210:213], v[12:15]
	v_mfma_f32_16x16x32_bf16 v[4:7], v[148:151], v[218:221], v[4:7]
	v_mfma_f32_16x16x32_bf16 v[0:3], v[156:159], v[218:221], v[0:3]
	s_setprio 0
	s_barrier
	s_add_u32 s4, s4, 0x100
	s_addc_u32 s5, s5, 0
	s_add_u32 s36, s36, 0x100
	s_addc_u32 s37, s37, 0
	s_cmp_ge_u32 s56, s47
	s_mov_b32 s34, s56
	s_cbranch_scc1 .Lafter_342

; #define PG8_BAR __builtin_amdgcn_s_barrier()
; template <class Epi>
; __device__ __forceinline__ void gemm_phase(LAS unsigned char* lds, const Gemm g, const StaticOrder& S, const Epi& E) {
;     ...
;         }
;         if (wr == 0) PG8_BAR;
;         E(acc, cur, wr, wc, fr, fq);
.Lafter_342:
	s_and_b64 vcc, exec, s[24:25]
	s_cbranch_vccz .LBB0_345
	s_barrier

; #define PG8_STAGE(bufoff, gbase, voff) do { _Pragma("unroll") for (int _i = 0; _i < 2; ++_i) \
;         __builtin_amdgcn_global_load_lds((const unsigned*)((const char*)(gbase) + (voff)[_i]), (LAS unsigned*)(lds + (bufoff) + ldsw + _i * 8192), 16, 0, 0); } while (0)
; #define PG8_LDA(dst, b, h) do { _Pragma("unroll") for (int m = 0; m < 4; ++m) _Pragma("unroll") for (int k = 0; k < 2; ++k) dst[m][k] = *(const LAS bf16x8*)(lds + PG8_SA(b, h) + aoff + m * 2048 + k * 1024); } while (0)
; #define PG8_LDB(dst, b, h) do { _Pragma("unroll") for (int n = 0; n < 2; ++n) _Pragma("unroll") for (int k = 0; k < 2; ++k) dst[n][k] = *(const LAS bf16x8*)(lds + PG8_SB(b, h) + boff + n * 2048 + k * 1024); } while (0)
; #define PG8_MMA(ai, bj, At, Bt) do { __builtin_amdgcn_s_setprio(1); _Pragma("unroll") for (int m = 0; m < 4; ++m) _Pragma("unroll") for (int n = 0; n < 2; ++n) _Pragma("unroll") for (int k = 0; k < 2; ++k) \
;         acc[ai][bj][m][n] = __builtin_amdgcn_mfma_f32_16x16x32_bf16(Bt[n][k], At[m][k], acc[ai][bj][m][n], 0, 0, 0); __builtin_amdgcn_s_setprio(0); } while (0)
; template <class Epi>
; __device__ __forceinline__ void gemm_phase(LAS unsigned char* lds, const Gemm g, const StaticOrder& S, const Epi& E) {
;     ...
;         for (int t = 0; t < nt; t += 2) {
;             const bool last = (t == nt - 2);
;             const char* a1 = cA + (size_t)(t + 1) * kstep;
;             const char* a2 = last ? nA : cA + (size_t)(t + 2) * kstep; const char* b2 = last ? nB : cB + (size_t)(t + 2) * kstep;
;             const char* a3 = a2 + kstep; const char* b3 = b2 + kstep;
;             PG8_LDB(B0, 0, 0); PG8_LDB(B1, 0, 1); PG8_SCHED; PG8_LDA(At, 0, 0); PG8_STAGE(PG8_SA(1, 1), a1 + hA, voffA);
;             PG8_WAIT_V(8); PG8_WAIT_L(0); PG8_BAR; PG8_MMA(0, 0, At, B0); PG8_MMA(0, 1, At, B1); PG8_BAR; PG8_SCHED;
;             PG8_LDA(At, 0, 1); PG8_STAGE(PG8_SB(0, 0), b2, voffB); PG8_STAGE(PG8_SB(0, 1), b2 + hB, voffB); PG8_STAGE(PG8_SA(0, 0), a2, voffA);
;             PG8_WAIT_V(8); PG8_WAIT_L(0); PG8_BAR; PG8_MMA(1, 0, At, B0); PG8_MMA(1, 1, At, B1); PG8_BAR; PG8_SCHED;
;     ...
; #pragma unroll
;         for (int a = 0; a < 2; ++a)
; #pragma unroll
;             for (int b = 0; b < 2; ++b)
; #pragma unroll
;                 for (int m = 0; m < 4; ++m)
; #pragma unroll
;                     for (int n = 0; n < 2; ++n) acc[a][b][m][n] = (f32x4){0.f, 0.f, 0.f, 0.f};
.LBB0_430:
	s_add_u32 s0, s40, 0x80080
	s_addc_u32 s1, s41, 0
	s_add_u32 s29, s38, 0x100
	s_addc_u32 s33, s39, 0
	s_mov_b32 s37, 0
	s_nop 0
.Lpeel_431:
	s_add_i32 m0, s49, 0xc000
	ds_read_b128 v[128:131], v240
	ds_read_b128 v[132:135], v240 offset:1024
	ds_read_b128 v[136:139], v240 offset:2048
	ds_read_b128 v[140:143], v240 offset:3072
	ds_read_b128 v[144:147], v240 offset:16384
	ds_read_b128 v[148:151], v240 offset:17408
	ds_read_b128 v[152:155], v240 offset:18432
	ds_read_b128 v[156:159], v240 offset:19456
	ds_read_b128 v[180:183], v209
	ds_read_b128 v[184:187], v209 offset:1024
	ds_read_b128 v[188:191], v209 offset:2048
	ds_read_b128 v[192:195], v209 offset:3072
	ds_read_b128 v[210:213], v209 offset:4096
	ds_read_b128 v[214:217], v209 offset:5120
	ds_read_b128 v[218:221], v209 offset:6144
	ds_read_b128 v[222:225], v209 offset:7168
	global_load_lds_dwordx4 v176, s[0:1]
	s_add_i32 m0, s49, 0xe000
	s_nop 0
	global_load_lds_dwordx4 v178, s[0:1]
	s_add_i32 s40, s37, 2
	s_add_u32 s38, s0, 0xfff80080
	s_addc_u32 s39, s1, -1
	s_add_i32 s41, 0, 0x10000
	s_cmp_eq_u32 s57, s37
	s_cselect_b32 s39, s31, s39
	s_cselect_b32 s38, s30, s38
	s_cselect_b32 s69, s35, s33
	s_cselect_b32 s68, s34, s29
	s_add_i32 s37, 0, 0x14000
	s_waitcnt vmcnt(8)
	s_waitcnt lgkmcnt(0)
	s_barrier
	s_setprio 1
	s_waitcnt lgkmcnt(0)
	v_mfma_f32_16x16x32_bf16 v[124:127], v[128:131], v[180:183], 0
	v_mfma_f32_16x16x32_bf16 v[120:123], v[136:139], v[180:183], 0
	v_mfma_f32_16x16x32_bf16 v[108:111], v[128:131], v[188:191], 0
	v_mfma_f32_16x16x32_bf16 v[104:107], v[136:139], v[188:191], 0
	v_mfma_f32_16x16x32_bf16 v[92:95], v[128:131], v[210:213], 0
	v_mfma_f32_16x16x32_bf16 v[88:91], v[136:139], v[210:213], 0
	v_mfma_f32_16x16x32_bf16 v[76:79], v[128:131], v[218:221], 0
	v_mfma_f32_16x16x32_bf16 v[72:75], v[136:139], v[218:221], 0
	v_mfma_f32_16x16x32_bf16 v[124:127], v[132:135], v[184:187], v[124:127]
	v_mfma_f32_16x16x32_bf16 v[120:123], v[140:143], v[184:187], v[120:123]
	v_mfma_f32_16x16x32_bf16 v[108:111], v[132:135], v[192:195], v[108:111]
	v_mfma_f32_16x16x32_bf16 v[104:107], v[140:143], v[192:195], v[104:107]
	v_mfma_f32_16x16x32_bf16 v[92:95], v[132:135], v[214:217], v[92:95]
	v_mfma_f32_16x16x32_bf16 v[88:91], v[140:143], v[214:217], v[88:91]
	v_mfma_f32_16x16x32_bf16 v[76:79], v[132:135], v[222:225], v[76:79]
	v_mfma_f32_16x16x32_bf16 v[72:75], v[140:143], v[222:225], v[72:75]
	s_setprio 0
	s_setprio 1
	v_mfma_f32_16x16x32_bf16 v[116:119], v[144:147], v[180:183], 0
	v_mfma_f32_16x16x32_bf16 v[112:115], v[152:155], v[180:183], 0
	v_mfma_f32_16x16x32_bf16 v[100:103], v[144:147], v[188:191], 0
	v_mfma_f32_16x16x32_bf16 v[96:99], v[152:155], v[188:191], 0
	v_mfma_f32_16x16x32_bf16 v[84:87], v[144:147], v[210:213], 0
	v_mfma_f32_16x16x32_bf16 v[80:83], v[152:155], v[210:213], 0
	v_mfma_f32_16x16x32_bf16 v[68:71], v[144:147], v[218:221], 0
	v_mfma_f32_16x16x32_bf16 v[64:67], v[152:155], v[218:221], 0
	v_mfma_f32_16x16x32_bf16 v[116:119], v[148:151], v[184:187], v[116:119]
	v_mfma_f32_16x16x32_bf16 v[112:115], v[156:159], v[184:187], v[112:115]
	v_mfma_f32_16x16x32_bf16 v[100:103], v[148:151], v[192:195], v[100:103]
	v_mfma_f32_16x16x32_bf16 v[96:99], v[156:159], v[192:195], v[96:99]
	v_mfma_f32_16x16x32_bf16 v[84:87], v[148:151], v[214:217], v[84:87]
	v_mfma_f32_16x16x32_bf16 v[80:83], v[156:159], v[214:217], v[80:83]
	v_mfma_f32_16x16x32_bf16 v[68:71], v[148:151], v[222:225], v[68:71]
	v_mfma_f32_16x16x32_bf16 v[64:67], v[156:159], v[222:225], v[64:67]
	s_setprio 0
	s_barrier
	ds_read_b128 v[180:183], v209 offset:16384
	ds_read_b128 v[184:187], v209 offset:17408
	ds_read_b128 v[188:191], v209 offset:18432
	ds_read_b128 v[192:195], v209 offset:19456
	ds_read_b128 v[210:213], v209 offset:20480
	ds_read_b128 v[214:217], v209 offset:21504
	ds_read_b128 v[218:221], v209 offset:22528
	ds_read_b128 v[222:225], v209 offset:23552
	s_add_i32 s41, s41, s48
	s_mov_b32 m0, s41
	s_add_i32 s37, s37, s48
	global_load_lds_dwordx4 v168, s[68:69]
	s_add_i32 m0, s41, 0x2000
	s_nop 0
	global_load_lds_dwordx4 v164, s[68:69]
	s_add_u32 s68, s68, s46
	s_addc_u32 s69, s69, 0
	s_mov_b32 m0, s37
	s_nop 0
	global_load_lds_dwordx4 v168, s[68:69]
	s_add_i32 m0, s37, 0x2000
	s_nop 0
	global_load_lds_dwordx4 v164, s[68:69]
	s_mov_b32 m0, s49
	s_nop 0
	global_load_lds_dwordx4 v160, s[38:39]
	s_mov_b32 m0, s50
	s_nop 0
	global_load_lds_dwordx4 v162, s[38:39]
	s_waitcnt vmcnt(8)
	s_waitcnt lgkmcnt(0)
	s_barrier
	s_setprio 1
	s_waitcnt lgkmcnt(0)
	v_mfma_f32_16x16x32_bf16 v[60:63], v[128:131], v[180:183], 0
	v_mfma_f32_16x16x32_bf16 v[56:59], v[136:139], v[180:183], 0
	v_mfma_f32_16x16x32_bf16 v[44:47], v[128:131], v[188:191], 0
	v_mfma_f32_16x16x32_bf16 v[40:43], v[136:139], v[188:191], 0
	v_mfma_f32_16x16x32_bf16 v[28:31], v[128:131], v[210:213], 0
	v_mfma_f32_16x16x32_bf16 v[24:27], v[136:139], v[210:213], 0
	v_mfma_f32_16x16x32_bf16 v[12:15], v[128:131], v[218:221], 0
	v_mfma_f32_16x16x32_bf16 v[8:11], v[136:139], v[218:221], 0
	v_mfma_f32_16x16x32_bf16 v[60:63], v[132:135], v[184:187], v[60:63]
	v_mfma_f32_16x16x32_bf16 v[56:59], v[140:143], v[184:187], v[56:59]
	v_mfma_f32_16x16x32_bf16 v[44:47], v[132:135], v[192:195], v[44:47]
	v_mfma_f32_16x16x32_bf16 v[40:43], v[140:143], v[192:195], v[40:43]
	v_mfma_f32_16x16x32_bf16 v[28:31], v[132:135], v[214:217], v[28:31]
	v_mfma_f32_16x16x32_bf16 v[24:27], v[140:143], v[214:217], v[24:27]
	v_mfma_f32_16x16x32_bf16 v[12:15], v[132:135], v[222:225], v[12:15]
	v_mfma_f32_16x16x32_bf16 v[8:11], v[140:143], v[222:225], v[8:11]
	s_setprio 0
	s_setprio 1
	v_mfma_f32_16x16x32_bf16 v[52:55], v[144:147], v[180:183], 0
	v_mfma_f32_16x16x32_bf16 v[48:51], v[152:155], v[180:183], 0
	v_mfma_f32_16x16x32_bf16 v[36:39], v[144:147], v[188:191], 0
	v_mfma_f32_16x16x32_bf16 v[32:35], v[152:155], v[188:191], 0
	v_mfma_f32_16x16x32_bf16 v[20:23], v[144:147], v[210:213], 0
	v_mfma_f32_16x16x32_bf16 v[16:19], v[152:155], v[210:213], 0
	v_mfma_f32_16x16x32_bf16 v[4:7], v[144:147], v[218:221], 0
	v_mfma_f32_16x16x32_bf16 v[0:3], v[152:155], v[218:221], 0
	v_mfma_f32_16x16x32_bf16 v[52:55], v[148:151], v[184:187], v[52:55]
	v_mfma_f32_16x16x32_bf16 v[48:51], v[156:159], v[184:187], v[48:51]
	v_mfma_f32_16x16x32_bf16 v[36:39], v[148:151], v[192:195], v[36:39]
	v_mfma_f32_16x16x32_bf16 v[32:35], v[156:159], v[192:195], v[32:35]
	v_mfma_f32_16x16x32_bf16 v[20:23], v[148:151], v[214:217], v[20:23]
	v_mfma_f32_16x16x32_bf16 v[16:19], v[156:159], v[214:217], v[16:19]
	v_mfma_f32_16x16x32_bf16 v[4:7], v[148:151], v[222:225], v[4:7]
	v_mfma_f32_16x16x32_bf16 v[0:3], v[156:159], v[222:225], v[0:3]
	s_setprio 0
	s_barrier
; #define PG8_STAGE(bufoff, gbase, voff) do { _Pragma("unroll") for (int _i = 0; _i < 2; ++_i) \
;         __builtin_amdgcn_global_load_lds((const unsigned*)((const char*)(gbase) + (voff)[_i]), (LAS unsigned*)(lds + (bufoff) + ldsw + _i * 8192), 16, 0, 0); } while (0)
; #define PG8_LDA(dst, b, h) do { _Pragma("unroll") for (int m = 0; m < 4; ++m) _Pragma("unroll") for (int k = 0; k < 2; ++k) dst[m][k] = *(const LAS bf16x8*)(lds + PG8_SA(b, h) + aoff + m * 2048 + k * 1024); } while (0)
; #define PG8_LDB(dst, b, h) do { _Pragma("unroll") for (int n = 0; n < 2; ++n) _Pragma("unroll") for (int k = 0; k < 2; ++k) dst[n][k] = *(const LAS bf16x8*)(lds + PG8_SB(b, h) + boff + n * 2048 + k * 1024); } while (0)
; #define PG8_MMA(ai, bj, At, Bt) do { __builtin_amdgcn_s_setprio(1); _Pragma("unroll") for (int m = 0; m < 4; ++m) _Pragma("unroll") for (int n = 0; n < 2; ++n) _Pragma("unroll") for (int k = 0; k < 2; ++k) \
;         acc[ai][bj][m][n] = __builtin_amdgcn_mfma_f32_16x16x32_bf16(Bt[n][k], At[m][k], acc[ai][bj][m][n], 0, 0, 0); __builtin_amdgcn_s_setprio(0); } while (0)
; #define PG8_WAIT_V(n) asm volatile("s_waitcnt vmcnt(" #n ")" ::: "memory")
; #define PG8_WAIT_L(n) asm volatile("s_waitcnt lgkmcnt(" #n ")" ::: "memory")
; #define PG8_BAR __builtin_amdgcn_s_barrier()
; #define PG8_SCHED __builtin_amdgcn_sched_barrier(0)
; template <class Epi>
; __device__ __forceinline__ void gemm_phase(LAS unsigned char* lds, const Gemm g, const StaticOrder& S, const Epi& E) {
;     ...
;             PG8_LDB(B0, 1, 0); PG8_LDB(B1, 1, 1); PG8_SCHED; PG8_LDA(At, 1, 0); PG8_STAGE(PG8_SA(0, 1), a2 + hA, voffA);
;             PG8_WAIT_V(8); PG8_WAIT_L(0); PG8_BAR; PG8_MMA(0, 0, At, B0); PG8_MMA(0, 1, At, B1); PG8_BAR; PG8_SCHED;
;             PG8_LDA(At, 1, 1); PG8_STAGE(PG8_SB(1, 0), b3, voffB); PG8_STAGE(PG8_SB(1, 1), b3 + hB, voffB); PG8_STAGE(PG8_SA(1, 0), a3, voffA);
;             PG8_WAIT_V(8); PG8_WAIT_L(0); PG8_BAR; PG8_MMA(1, 0, At, B0); PG8_MMA(1, 1, At, B1); PG8_BAR; PG8_SCHED;
;         }
	ds_read_b128 v[128:131], v240 offset:32768
	ds_read_b128 v[132:135], v240 offset:33792
	ds_read_b128 v[136:139], v240 offset:34816
	ds_read_b128 v[140:143], v240 offset:35840
	ds_read_b128 v[144:147], v240 offset:49152
	ds_read_b128 v[148:151], v240 offset:50176
	ds_read_b128 v[152:155], v240 offset:51200
	ds_read_b128 v[156:159], v240 offset:52224
	ds_read_b128 v[180:183], v209 offset:32768
	ds_read_b128 v[184:187], v209 offset:33792
	ds_read_b128 v[188:191], v209 offset:34816
	ds_read_b128 v[192:195], v209 offset:35840
	ds_read_b128 v[210:213], v209 offset:36864
	ds_read_b128 v[214:217], v209 offset:37888
	ds_read_b128 v[218:221], v209 offset:38912
	ds_read_b128 v[222:225], v209 offset:39936
	s_add_u32 s38, s38, 0x80000
	s_addc_u32 s39, s39, 0
	s_mov_b32 m0, s51
	s_add_i32 s41, 0, 0x18000
	global_load_lds_dwordx4 v160, s[38:39]
	s_mov_b32 m0, s52
	s_nop 0
	global_load_lds_dwordx4 v162, s[38:39]
	s_waitcnt vmcnt(8)
	s_waitcnt lgkmcnt(0)
	s_barrier
	s_setprio 1
	s_waitcnt lgkmcnt(0)
	v_mfma_f32_16x16x32_bf16 v[124:127], v[128:131], v[180:183], v[124:127]
	v_mfma_f32_16x16x32_bf16 v[120:123], v[136:139], v[180:183], v[120:123]
	v_mfma_f32_16x16x32_bf16 v[108:111], v[128:131], v[188:191], v[108:111]
	v_mfma_f32_16x16x32_bf16 v[104:107], v[136:139], v[188:191], v[104:107]
	v_mfma_f32_16x16x32_bf16 v[92:95], v[128:131], v[210:213], v[92:95]
	v_mfma_f32_16x16x32_bf16 v[88:91], v[136:139], v[210:213], v[88:91]
	v_mfma_f32_16x16x32_bf16 v[76:79], v[128:131], v[218:221], v[76:79]
	v_mfma_f32_16x16x32_bf16 v[72:75], v[136:139], v[218:221], v[72:75]
	v_mfma_f32_16x16x32_bf16 v[124:127], v[132:135], v[184:187], v[124:127]
	v_mfma_f32_16x16x32_bf16 v[120:123], v[140:143], v[184:187], v[120:123]
	v_mfma_f32_16x16x32_bf16 v[108:111], v[132:135], v[192:195], v[108:111]
	v_mfma_f32_16x16x32_bf16 v[104:107], v[140:143], v[192:195], v[104:107]
	v_mfma_f32_16x16x32_bf16 v[92:95], v[132:135], v[214:217], v[92:95]
	v_mfma_f32_16x16x32_bf16 v[88:91], v[140:143], v[214:217], v[88:91]
	v_mfma_f32_16x16x32_bf16 v[76:79], v[132:135], v[222:225], v[76:79]
	v_mfma_f32_16x16x32_bf16 v[72:75], v[140:143], v[222:225], v[72:75]
	s_setprio 0
	s_setprio 1
	v_mfma_f32_16x16x32_bf16 v[116:119], v[144:147], v[180:183], v[116:119]
	v_mfma_f32_16x16x32_bf16 v[112:115], v[152:155], v[180:183], v[112:115]
	v_mfma_f32_16x16x32_bf16 v[100:103], v[144:147], v[188:191], v[100:103]
	v_mfma_f32_16x16x32_bf16 v[96:99], v[152:155], v[188:191], v[96:99]
	v_mfma_f32_16x16x32_bf16 v[84:87], v[144:147], v[210:213], v[84:87]
	v_mfma_f32_16x16x32_bf16 v[80:83], v[152:155], v[210:213], v[80:83]
	v_mfma_f32_16x16x32_bf16 v[68:71], v[144:147], v[218:221], v[68:71]
	v_mfma_f32_16x16x32_bf16 v[64:67], v[152:155], v[218:221], v[64:67]
	v_mfma_f32_16x16x32_bf16 v[116:119], v[148:151], v[184:187], v[116:119]
	v_mfma_f32_16x16x32_bf16 v[112:115], v[156:159], v[184:187], v[112:115]
	v_mfma_f32_16x16x32_bf16 v[100:103], v[148:151], v[192:195], v[100:103]
	v_mfma_f32_16x16x32_bf16 v[96:99], v[156:159], v[192:195], v[96:99]
	v_mfma_f32_16x16x32_bf16 v[84:87], v[148:151], v[214:217], v[84:87]
	v_mfma_f32_16x16x32_bf16 v[80:83], v[156:159], v[214:217], v[80:83]
	v_mfma_f32_16x16x32_bf16 v[68:71], v[148:151], v[222:225], v[68:71]
	v_mfma_f32_16x16x32_bf16 v[64:67], v[156:159], v[222:225], v[64:67]
	s_setprio 0
	s_barrier
	ds_read_b128 v[180:183], v209 offset:49152
	ds_read_b128 v[184:187], v209 offset:50176
	ds_read_b128 v[188:191], v209 offset:51200
	ds_read_b128 v[192:195], v209 offset:52224
	ds_read_b128 v[210:213], v209 offset:53248
	ds_read_b128 v[214:217], v209 offset:54272
	ds_read_b128 v[218:221], v209 offset:55296
	ds_read_b128 v[222:225], v209 offset:56320
	s_add_i32 s41, s41, s48
	s_add_i32 m0, s41, 0x4000
	s_nop 0
	global_load_lds_dwordx4 v241, s[68:69]
	s_add_i32 m0, s41, 0x6000
	s_nop 0
	global_load_lds_dwordx4 v242, s[68:69]
	s_sub_u32 s68, s68, s46
	s_subb_u32 s69, s69, 0
	s_mov_b32 m0, s41
	s_nop 0
	global_load_lds_dwordx4 v241, s[68:69]
	s_add_i32 m0, s41, 0x2000
	s_nop 0
	global_load_lds_dwordx4 v242, s[68:69]
	s_sub_u32 s38, s38, 0x80000
	s_subb_u32 s39, s39, 0
	s_mov_b32 m0, s55
	s_nop 0
	global_load_lds_dwordx4 v243, s[38:39]
	s_mov_b32 m0, s56
	s_nop 0
	global_load_lds_dwordx4 v244, s[38:39]
	s_waitcnt vmcnt(8)
	s_waitcnt lgkmcnt(0)
	s_barrier
	s_setprio 1
	s_waitcnt lgkmcnt(0)
	v_mfma_f32_16x16x32_bf16 v[60:63], v[128:131], v[180:183], v[60:63]
	v_mfma_f32_16x16x32_bf16 v[56:59], v[136:139], v[180:183], v[56:59]
	v_mfma_f32_16x16x32_bf16 v[44:47], v[128:131], v[188:191], v[44:47]
	v_mfma_f32_16x16x32_bf16 v[40:43], v[136:139], v[188:191], v[40:43]
	v_mfma_f32_16x16x32_bf16 v[28:31], v[128:131], v[210:213], v[28:31]
	v_mfma_f32_16x16x32_bf16 v[24:27], v[136:139], v[210:213], v[24:27]
	v_mfma_f32_16x16x32_bf16 v[12:15], v[128:131], v[218:221], v[12:15]
	v_mfma_f32_16x16x32_bf16 v[8:11], v[136:139], v[218:221], v[8:11]
	v_mfma_f32_16x16x32_bf16 v[60:63], v[132:135], v[184:187], v[60:63]
	v_mfma_f32_16x16x32_bf16 v[56:59], v[140:143], v[184:187], v[56:59]
	v_mfma_f32_16x16x32_bf16 v[44:47], v[132:135], v[192:195], v[44:47]
	v_mfma_f32_16x16x32_bf16 v[40:43], v[140:143], v[192:195], v[40:43]
	v_mfma_f32_16x16x32_bf16 v[28:31], v[132:135], v[214:217], v[28:31]
	v_mfma_f32_16x16x32_bf16 v[24:27], v[140:143], v[214:217], v[24:27]
	v_mfma_f32_16x16x32_bf16 v[12:15], v[132:135], v[222:225], v[12:15]
	v_mfma_f32_16x16x32_bf16 v[8:11], v[140:143], v[222:225], v[8:11]
	s_setprio 0
	s_setprio 1
	v_mfma_f32_16x16x32_bf16 v[52:55], v[144:147], v[180:183], v[52:55]
	v_mfma_f32_16x16x32_bf16 v[48:51], v[152:155], v[180:183], v[48:51]
	v_mfma_f32_16x16x32_bf16 v[36:39], v[144:147], v[188:191], v[36:39]
	v_mfma_f32_16x16x32_bf16 v[32:35], v[152:155], v[188:191], v[32:35]
	v_mfma_f32_16x16x32_bf16 v[20:23], v[144:147], v[210:213], v[20:23]
	v_mfma_f32_16x16x32_bf16 v[16:19], v[152:155], v[210:213], v[16:19]
	v_mfma_f32_16x16x32_bf16 v[4:7], v[144:147], v[218:221], v[4:7]
	v_mfma_f32_16x16x32_bf16 v[0:3], v[152:155], v[218:221], v[0:3]
	v_mfma_f32_16x16x32_bf16 v[52:55], v[148:151], v[184:187], v[52:55]
	v_mfma_f32_16x16x32_bf16 v[48:51], v[156:159], v[184:187], v[48:51]
	v_mfma_f32_16x16x32_bf16 v[36:39], v[148:151], v[192:195], v[36:39]
	v_mfma_f32_16x16x32_bf16 v[32:35], v[156:159], v[192:195], v[32:35]
	v_mfma_f32_16x16x32_bf16 v[20:23], v[148:151], v[214:217], v[20:23]
	v_mfma_f32_16x16x32_bf16 v[16:19], v[156:159], v[214:217], v[16:19]
	v_mfma_f32_16x16x32_bf16 v[4:7], v[148:151], v[222:225], v[4:7]
	v_mfma_f32_16x16x32_bf16 v[0:3], v[156:159], v[222:225], v[0:3]
	s_setprio 0
	s_barrier
	s_add_u32 s0, s0, 0x100
	s_addc_u32 s1, s1, 0
	s_add_u32 s29, s29, 0x100
	s_addc_u32 s33, s33, 0
	s_cmp_ge_u32 s40, s54
	s_mov_b32 s37, s40
	s_cbranch_scc1 .Lafter_431
